# depthwise-conv phase: token index bit-permuted so each workgroup convolves tokens of M-tiles owned by its XCD (producer z rows and consumer gate-GEMM rows both local)
# baseline (speedup 1.0000x reference)
;   DI bf16_t* z() const { return (bf16_t*)(ws + OFF_Z); }
;   DI bf16_t* xc() const { return (bf16_t*)(ws + OFF_Q1); }
; DI float bflo(unsigned u) { return __uint_as_float(u << 16); }
; DI float bfhi(unsigned u) { return __uint_as_float(u & 0xffff0000u); }
; DI int otid() { int t = threadIdx.x; asm volatile("" : "+v"(t)); return t; }
; DI void phase_conv(const Params& p) {
;   for (int i = blockIdx.x * NTH + otid(); i < T * 128; i += gridDim.x * NTH) {
;     const int tok = i >> 7, c = (i & 127) * 8, s = tok & 4095;
;     float o[8];
; #pragma unroll
;     for (int e = 0; e < 8; ++e) o[e] = p.conv_b[c + e];
; #pragma unroll
;     for (int k = 0; k < 4; ++k) {
;       const int ss = s - 3 + k;
;       if (ss < 0) continue;
;       const u32x4 v = *(const u32x4*)(p.z() + (size_t)(tok - 3 + k) * LDZ0 + c);
;       const float* wk = p.conv_w + k * 1024 + c;
;       o[0] += wk[0] * bflo(v.x); o[1] += wk[1] * bfhi(v.x); o[2] += wk[2] * bflo(v.y); o[3] += wk[3] * bfhi(v.y);
;       o[4] += wk[4] * bflo(v.z); o[5] += wk[5] * bfhi(v.z); o[6] += wk[6] * bflo(v.w); o[7] += wk[7] * bfhi(v.w);
;     }
;     u32x4 w; w.x = pk_bf16(o[0], o[1]); w.y = pk_bf16(o[2], o[3]); w.z = pk_bf16(o[4], o[5]); w.w = pk_bf16(o[6], o[7]);
;     *(u32x4*)(p.xc() + (size_t)tok * 1024 + c) = w;
;   }
.LBB0_188:
	v_and_b32_e32 v10, 0x3f8, v19
	v_lshlrev_b32_e32 v8, 2, v10
	global_load_dwordx4 v[0:3], v8, s[78:79] offset:16
	global_load_dwordx4 v[4:7], v8, s[78:79]
	v_ashrrev_i32_e32 v12, 7, v18
	v_and_b32_e32 v20, 3, v12
	v_bfe_u32 v21, v12, 10, 4
	v_lshl_or_b32 v20, v21, 2, v20
	v_bfe_u32 v21, v12, 5, 2
	v_lshl_or_b32 v20, v21, 6, v20
	v_bfe_u32 v21, v12, 2, 3
	v_lshl_or_b32 v20, v21, 8, v20
	v_bfe_u32 v21, v12, 7, 3
	v_lshl_or_b32 v12, v21, 11, v20
	v_and_b32_e32 v13, 0xfff, v12
	v_lshlrev_b32_e32 v10, 1, v10
	v_mov_b32_e32 v11, v9
	v_lshl_add_u64 v[16:17], s[2:3], 0, v[10:11]
	v_lshl_add_u64 v[14:15], s[76:77], 0, v[8:9]
	v_cmp_lt_u32_e32 vcc, 2, v13
	s_and_saveexec_b64 s[14:15], vcc
	s_cbranch_execnz .LBB0_191
	s_or_b64 exec, exec, s[14:15]
	v_cmp_lt_u32_e32 vcc, 1, v13
	s_and_saveexec_b64 s[14:15], vcc
	s_cbranch_execnz .LBB0_192
